# GDN state-scan wave runs at s_setprio 3 (it is the serial pole of the phase, competing with attention waves for issue)
# speedup vs baseline: 1.0114x; 1.0114x over previous
; #define LAS __attribute__((address_space(3)))
; DI f32x16 zero16() { f32x16 z; for (int i = 0; i < 16; ++i) z[i] = 0.f; return z; }
; DI void phase_scan(KArgs args, LAS unsigned char* L, const Ctx& c) {
;     ...
;     const int nwu = c.nseq * 24, wu = c.bid;
;     if (wu < nwu && c.wave == 0) {
;         const int lane = c.lane;
;         const int chain = wu >> 1, nt = wu & 1, seq = chain / 12, rem = chain % 12, head = rem >> 1, dir = rem & 1;
;         const int nch = c.seqlen >> 6, gch0 = seq * nch;
;         unsigned char* GS = BIGP(unsigned char, B_GSCR);
;         f32x16 S[2]; S[0] = zero16(); S[1] = zero16();
;         bf16x8 A[2][2][4]; u32x4 cm[2][2][2];
;         const long gstep = (long)(dir ? -1 : 1) * 12 * GSTRIDE;
;         const unsigned char* G0 = GS + (size_t)(((gch0 + (dir ? nch - 1 : 0)) * 6 + head) * 2 + dir) * GSTRIDE;
;         unsigned char* Gs = (unsigned char*)G0;
;         float glv[4];
; #pragma unroll
;         for (int q = 0; q < 4; ++q) { const int sq = q * 64 + lane; glv[q] = *(const float*)(G0 + (long)(sq < nch ? sq : nch - 1) * gstep + 40960); }
;         LAS unsigned char* RING = L + 81920;
;         int dslot = 0, rslot = 0, dstage = 0;
;     ...
;         SCAN_DMA(); SCAN_DMA(); SCAN_DMA(); SCAN_DMA(); SCAN_DMA();
;         asm volatile("s_waitcnt vmcnt(48)" ::: "memory"); SCAN_LOAD(0);
;         asm volatile("s_waitcnt vmcnt(36)" ::: "memory"); SCAN_LOAD(1);
.LBB0_646:
	s_movk_i32 s33, 0x600
	s_and_b64 vcc, exec, s[0:1]
	s_cbranch_vccz .LBB0_946
	v_readlane_b32 s2, v254, 23
	s_lshr_b32 s30, s60, 6
	v_readlane_b32 s3, v254, 24
	s_and_b64 s[0:1], s[2:3], exec
	s_cselect_b32 s0, 6, 8
	s_add_i32 s31, s30, -1
	v_writelane_b32 v254, s0, 32
	s_and_b64 s[0:1], s[2:3], exec
	s_cselect_b32 s2, 0xc0, 24
	s_cmp_lt_u32 s61, 64
	s_cselect_b64 s[0:1], -1, 0
	s_cmp_lt_i32 s68, s2
	s_cselect_b64 s[2:3], -1, 0
	s_and_b64 s[0:1], s[2:3], s[0:1]
	s_andn2_b64 vcc, exec, s[0:1]
	s_movk_i32 s27, 0x90
	v_readlane_b32 s28, v254, 27
	v_readlane_b32 s29, v254, 29
	s_cbranch_vccnz .LBB0_651
	s_setprio 3
	s_ashr_i32 s0, s68, 1
	s_mul_hi_i32 s1, s0, 0x2aaaaaab
	s_lshr_b32 s2, s1, 31
	s_ashr_i32 s1, s1, 1
	s_add_i32 s1, s1, s2
	s_mul_i32 s2, s1, 12
	s_sub_i32 s2, s0, s2
	v_readlane_b32 s4, v254, 32
	s_bfe_i32 s3, s2, 0x10000
	s_and_b32 s0, s2, 1
	s_lshl_b32 s4, s1, s4
	s_cmp_eq_u32 s0, 0
	s_mov_b32 s0, 0x78c00
	s_cselect_b32 s1, 0, -1
	s_cselect_b32 s0, s0, 0xfff87400
	s_and_b32 s3, s3, s31
	s_add_i32 s3, s3, s4
	s_mul_i32 s3, s3, 12
	s_add_i32 s24, s3, s2
	s_mul_hi_i32 s23, s24, 0xa100
	s_mul_i32 s24, s24, 0xa100
	s_waitcnt lgkmcnt(0)
	s_add_u32 s6, s72, s24
	s_addc_u32 s7, s73, s23
	s_add_u32 s2, s6, 0x37800000
	s_addc_u32 s3, s7, 0
	v_min_i32_e32 v1, s31, v28
	v_mov_b64_e32 v[4:5], s[2:3]
	v_mad_u64_u32 v[6:7], s[4:5], s0, v1, v[4:5]
	v_mad_i32_i24 v1, s1, v1, v7
	v_or_b32_e32 v7, 64, v28
	v_min_i32_e32 v2, s31, v7
	v_mad_u64_u32 v[8:9], s[4:5], s0, v2, v[4:5]
	v_or_b32_e32 v12, 0x80, v28
	v_mad_i32_i24 v9, s1, v2, v9
	v_min_i32_e32 v2, s31, v12
	v_mad_u64_u32 v[10:11], s[4:5], s0, v2, v[4:5]
	v_or_b32_e32 v13, 0xc0, v28
	v_mad_i32_i24 v11, s1, v2, v11
	v_min_i32_e32 v2, s31, v13
	v_mad_u64_u32 v[4:5], s[4:5], s0, v2, v[4:5]
	s_add_u32 s20, s6, 0x37802000
	s_addc_u32 s21, s7, 0
	s_lshl_b32 s4, s68, 12
	s_and_b32 s25, s4, 0x1000
	s_add_u32 s18, s2, s0
	s_addc_u32 s19, s3, s1
	s_add_u32 s16, s18, 0x2000
	s_addc_u32 s17, s19, 0
	s_add_u32 s14, s18, s0
	s_addc_u32 s15, s19, s1
	s_add_u32 s12, s14, 0x2000
	s_addc_u32 s13, s15, 0
	s_add_u32 s10, s14, s0
	s_addc_u32 s11, s15, s1
	s_mov_b32 s26, 0xa000
	s_add_u32 s8, s10, 0x2000
	v_add_co_u32_e32 v6, vcc, s26, v6
	v_lshlrev_b32_e32 v148, 4, v7
	s_addc_u32 s9, s11, 0
	v_addc_co_u32_e32 v7, vcc, 0, v1, vcc
	s_add_u32 s6, s10, s0
	v_add_co_u32_e32 v8, vcc, s26, v8
	s_addc_u32 s7, s11, s1
	s_nop 0
	v_addc_co_u32_e32 v9, vcc, 0, v9, vcc
	s_add_u32 s4, s6, 0x2000
	v_add_co_u32_e32 v10, vcc, s26, v10
	s_addc_u32 s5, s7, 0
	s_add_i32 s22, 0, 0x14000
	v_addc_co_u32_e32 v11, vcc, 0, v11, vcc
	v_mad_i32_i24 v5, s1, v2, v5
	v_lshlrev_b32_e32 v2, 4, v28
	v_add_co_u32_e32 v4, vcc, s26, v4
	s_mov_b32 m0, s22
	v_readlane_b32 s26, v253, 5
	v_addc_co_u32_e32 v5, vcc, 0, v5, vcc
	global_load_dword v1, v[6:7], off
	global_load_dword v168, v[8:9], off
	global_load_dword v169, v[10:11], off
	global_load_dword v170, v[4:5], off
	v_lshlrev_b32_e32 v150, 4, v12
	global_load_lds_dwordx4 v2, s[2:3]
	s_mov_b32 m0, s26
	v_readlane_b32 s26, v253, 6
	global_load_lds_dwordx4 v148, s[2:3]
	s_mov_b32 m0, s26
	v_readlane_b32 s26, v253, 7
	v_lshlrev_b32_e32 v152, 4, v13
	global_load_lds_dwordx4 v150, s[2:3]
	s_mov_b32 m0, s26
	v_readlane_b32 s26, v253, 8
	v_or_b32_e32 v154, 0x1000, v2
	global_load_lds_dwordx4 v152, s[2:3]
	s_mov_b32 m0, s26
	v_readlane_b32 s26, v253, 9
	v_or_b32_e32 v156, 0x1400, v2
	global_load_lds_dwordx4 v154, s[2:3]
	s_mov_b32 m0, s26
	v_readlane_b32 s26, v253, 10
	v_or_b32_e32 v158, 0x1800, v2
	global_load_lds_dwordx4 v156, s[2:3]
	s_mov_b32 m0, s26
	v_readlane_b32 s26, v253, 11
	v_or_b32_e32 v160, 0x1c00, v2
	v_lshl_or_b32 v162, v28, 5, s25
	v_mov_b32_e32 v163, v3
	global_load_lds_dwordx4 v158, s[2:3]
	s_mov_b32 m0, s26
	v_lshl_add_u64 v[12:13], s[20:21], 0, v[162:163]
	global_load_lds_dwordx4 v160, s[2:3]
	s_add_i32 m0, 0, 0x16000
	v_readlane_b32 s26, v253, 12
	v_lshl_add_u64 v[12:13], v[12:13], 0, 16
	global_load_lds_dwordx4 v162, s[20:21]
	s_mov_b32 m0, s26
	v_readlane_b32 s26, v253, 13
	v_or_b32_e32 v164, 0x800, v162
	v_mov_b32_e32 v165, v3
	global_load_lds_dwordx4 v[12:13], off
	s_mov_b32 m0, s26
	v_lshl_add_u64 v[14:15], s[20:21], 0, v[164:165]
	global_load_lds_dwordx4 v164, s[20:21]
	v_readlane_b32 s20, v253, 14
	v_lshl_add_u64 v[14:15], v[14:15], 0, 16
	s_mov_b32 m0, s20
	v_readlane_b32 s21, v253, 15
	global_load_lds_dwordx4 v[14:15], off
	s_mov_b32 m0, s21
	v_readlane_b32 s20, v253, 16
	global_load_lds_dwordx4 v2, s[18:19]
	s_mov_b32 m0, s20
	v_readlane_b32 s20, v253, 17
	global_load_lds_dwordx4 v148, s[18:19]
	s_mov_b32 m0, s20
	v_readlane_b32 s20, v253, 18
	global_load_lds_dwordx4 v150, s[18:19]
	s_mov_b32 m0, s20
	v_readlane_b32 s20, v253, 19
	global_load_lds_dwordx4 v152, s[18:19]
	s_add_i32 m0, 0, 0x18000
	v_lshl_add_u64 v[16:17], s[16:17], 0, v[162:163]
	global_load_lds_dwordx4 v154, s[18:19]
	s_mov_b32 m0, s20
	v_readlane_b32 s20, v253, 4
	global_load_lds_dwordx4 v156, s[18:19]
	s_mov_b32 m0, s20
	v_readlane_b32 s20, v253, 20
	global_load_lds_dwordx4 v158, s[18:19]
	s_mov_b32 m0, s20
	v_lshl_add_u64 v[16:17], v[16:17], 0, 16
	global_load_lds_dwordx4 v160, s[18:19]
	s_add_i32 m0, 0, 0x19000
	v_readlane_b32 s18, v253, 21
	global_load_lds_dwordx4 v162, s[16:17]
	s_mov_b32 m0, s18
	v_readlane_b32 s18, v253, 22
	global_load_lds_dwordx4 v[16:17], off
	s_mov_b32 m0, s18
	v_lshl_add_u64 v[18:19], s[16:17], 0, v[164:165]
	global_load_lds_dwordx4 v164, s[16:17]
	v_readlane_b32 s16, v253, 23
	v_lshl_add_u64 v[18:19], v[18:19], 0, 16
	s_mov_b32 m0, s16
	v_readlane_b32 s16, v253, 24
	global_load_lds_dwordx4 v[18:19], off
	s_add_i32 m0, 0, 0x1a000
	v_lshl_add_u64 v[20:21], s[12:13], 0, v[162:163]
; #define LAS __attribute__((address_space(3)))
; DI void phase_scan(KArgs args, LAS unsigned char* L, const Ctx& c) {
;     ...
;         for (int q = 0; q < 4; ++q) { const int sq = q * 64 + lane; glv[q] = *(const float*)(G0 + (long)(sq < nch ? sq : nch - 1) * gstep + 40960); }
;         LAS unsigned char* RING = L + 81920;
;         int dslot = 0, rslot = 0, dstage = 0;
;     ...
;         SCAN_DMA(); SCAN_DMA(); SCAN_DMA(); SCAN_DMA(); SCAN_DMA();
;         asm volatile("s_waitcnt vmcnt(48)" ::: "memory"); SCAN_LOAD(0);
;         asm volatile("s_waitcnt vmcnt(36)" ::: "memory"); SCAN_LOAD(1);
	global_load_lds_dwordx4 v2, s[14:15]
	s_mov_b32 m0, s16
	v_readlane_b32 s16, v253, 25
	global_load_lds_dwordx4 v148, s[14:15]
	s_mov_b32 m0, s16
	v_readlane_b32 s16, v253, 26
	global_load_lds_dwordx4 v150, s[14:15]
	s_mov_b32 m0, s16
	v_readlane_b32 s16, v253, 27
	global_load_lds_dwordx4 v152, s[14:15]
	s_mov_b32 m0, s16
	v_readlane_b32 s16, v253, 28
	global_load_lds_dwordx4 v154, s[14:15]
	s_mov_b32 m0, s16
	v_readlane_b32 s16, v253, 29
	global_load_lds_dwordx4 v156, s[14:15]
	s_mov_b32 m0, s16
	v_readlane_b32 s16, v253, 30
	global_load_lds_dwordx4 v158, s[14:15]
	s_mov_b32 m0, s16
	v_lshl_add_u64 v[20:21], v[20:21], 0, 16
	global_load_lds_dwordx4 v160, s[14:15]
	s_add_i32 m0, 0, 0x1c000
	v_readlane_b32 s14, v253, 31
	global_load_lds_dwordx4 v162, s[12:13]
	s_mov_b32 m0, s14
	v_readlane_b32 s14, v253, 32
	global_load_lds_dwordx4 v[20:21], off
	s_mov_b32 m0, s14
	v_lshl_add_u64 v[22:23], s[12:13], 0, v[164:165]
	global_load_lds_dwordx4 v164, s[12:13]
	v_readlane_b32 s12, v253, 33
	v_lshl_add_u64 v[22:23], v[22:23], 0, 16
	s_mov_b32 m0, s12
	v_readlane_b32 s12, v253, 34
	global_load_lds_dwordx4 v[22:23], off
	s_mov_b32 m0, s12
	v_readlane_b32 s12, v253, 35
	global_load_lds_dwordx4 v2, s[10:11]
	s_mov_b32 m0, s12
	v_readlane_b32 s12, v253, 36
	global_load_lds_dwordx4 v148, s[10:11]
	s_mov_b32 m0, s12
	v_readlane_b32 s12, v253, 37
	global_load_lds_dwordx4 v150, s[10:11]
	s_mov_b32 m0, s12
	v_readlane_b32 s12, v253, 38
	global_load_lds_dwordx4 v152, s[10:11]
	s_add_i32 m0, 0, 0x1e000
	v_lshl_add_u64 v[24:25], s[8:9], 0, v[162:163]
	global_load_lds_dwordx4 v154, s[10:11]
	s_mov_b32 m0, s12
	v_readlane_b32 s12, v253, 39
	global_load_lds_dwordx4 v156, s[10:11]
	s_mov_b32 m0, s12
	v_readlane_b32 s12, v253, 40
	global_load_lds_dwordx4 v158, s[10:11]
	s_mov_b32 m0, s12
	v_lshl_add_u64 v[24:25], v[24:25], 0, 16
	global_load_lds_dwordx4 v160, s[10:11]
	v_readlane_b32 s10, v253, 41
	s_mov_b32 m0, s10
	v_readlane_b32 s10, v253, 42
	global_load_lds_dwordx4 v162, s[8:9]
	s_mov_b32 m0, s10
	v_readlane_b32 s10, v253, 43
	global_load_lds_dwordx4 v[24:25], off
	s_mov_b32 m0, s10
	v_lshl_add_u64 v[26:27], s[8:9], 0, v[164:165]
	global_load_lds_dwordx4 v164, s[8:9]
	v_readlane_b32 s8, v253, 44
	v_lshl_add_u64 v[26:27], v[26:27], 0, 16
	s_mov_b32 m0, s8
	v_readlane_b32 s8, v253, 45
	global_load_lds_dwordx4 v[26:27], off
	s_add_i32 m0, 0, 0x20000
	v_lshl_add_u64 v[28:29], s[4:5], 0, v[162:163]
	global_load_lds_dwordx4 v2, s[6:7]
	s_mov_b32 m0, s8
	v_readlane_b32 s8, v253, 46
	global_load_lds_dwordx4 v148, s[6:7]
	s_mov_b32 m0, s8
	v_readlane_b32 s8, v253, 47
	global_load_lds_dwordx4 v150, s[6:7]
	s_mov_b32 m0, s8
	v_readlane_b32 s8, v253, 48
	global_load_lds_dwordx4 v152, s[6:7]
	s_mov_b32 m0, s8
	v_readlane_b32 s8, v253, 49
	global_load_lds_dwordx4 v154, s[6:7]
	s_mov_b32 m0, s8
	v_readlane_b32 s8, v253, 50
	global_load_lds_dwordx4 v156, s[6:7]
	s_mov_b32 m0, s8
	v_readlane_b32 s8, v253, 51
	global_load_lds_dwordx4 v158, s[6:7]
	s_mov_b32 m0, s8
	v_lshl_add_u64 v[28:29], v[28:29], 0, 16
	global_load_lds_dwordx4 v160, s[6:7]
	s_add_i32 m0, 0, 0x22000
	v_readlane_b32 s6, v253, 52
	global_load_lds_dwordx4 v162, s[4:5]
	s_mov_b32 m0, s6
	v_readlane_b32 s6, v253, 53
	global_load_lds_dwordx4 v[28:29], off
	s_mov_b32 m0, s6
	v_lshl_add_u64 v[30:31], s[4:5], 0, v[164:165]
	global_load_lds_dwordx4 v164, s[4:5]
	v_readlane_b32 s4, v253, 54
	v_lshl_add_u64 v[30:31], v[30:31], 0, 16
	s_mov_b32 m0, s4
	v_add_u32_e32 v171, s22, v2
	global_load_lds_dwordx4 v[30:31], off
	s_waitcnt vmcnt(48)
	ds_read_b128 v[76:79], v171
	ds_read_b128 v[80:83], v171 offset:1024
	ds_read_b128 v[84:87], v171 offset:2048
	ds_read_b128 v[88:91], v171 offset:3072
	ds_read_b128 v[96:99], v171 offset:8192
	ds_read_b128 v[92:95], v171 offset:9216
	ds_read_b128 v[36:39], v171 offset:4096
	ds_read_b128 v[40:43], v171 offset:5120
	ds_read_b128 v[44:47], v171 offset:6144
	ds_read_b128 v[48:51], v171 offset:7168
	ds_read_b128 v[72:75], v171 offset:10240
	ds_read_b128 v[52:55], v171 offset:11264
	s_waitcnt vmcnt(36)
	v_add_u32_e32 v4, s21, v2
	s_waitcnt vmcnt(0)
	ds_read_b128 v[100:103], v4 offset:11264
	ds_read_b128 v[104:107], v4 offset:10240
	ds_read_b128 v[56:59], v4 offset:7168
	ds_read_b128 v[60:63], v4 offset:6144
	ds_read_b128 v[64:67], v4 offset:5120
	ds_read_b128 v[68:71], v4 offset:4096
	ds_read_b128 v[124:127], v4 offset:9216
	ds_read_b128 v[128:131], v4 offset:8192
	ds_read_b128 v[108:111], v4 offset:3072
	ds_read_b128 v[112:115], v4 offset:2048
	ds_read_b128 v[116:119], v4 offset:1024
	ds_read_b128 v[120:123], v4
	s_add_u32 s4, s24, s25
	s_addc_u32 s5, s23, 0
	s_add_u32 s4, s72, s4
	s_addc_u32 s5, s73, s5
	v_lshl_add_u64 v[4:5], s[4:5], 0, v[2:3]
	s_mov_b64 s[4:5], 0x37808800
	v_lshl_add_u64 v[166:167], v[4:5], 0, s[4:5]
	v_mov_b32_e32 v4, 0
	s_mov_b32 s11, 0
	v_mov_b32_e32 v149, v3
	v_mov_b32_e32 v151, v3
	v_mov_b32_e32 v153, v3
	v_mov_b32_e32 v155, v3
	v_mov_b32_e32 v157, v3
	v_mov_b32_e32 v159, v3
	v_mov_b32_e32 v161, v3
	s_lshl_b64 s[8:9], s[0:1], 1
	s_mov_b32 s12, 2
	s_mov_b32 s10, 6
	v_mov_b32_e32 v5, v4
	v_mov_b32_e32 v6, v4
	v_mov_b32_e32 v7, v4
	v_mov_b32_e32 v8, v4
	v_mov_b32_e32 v9, v4
	v_mov_b32_e32 v10, v4
	v_mov_b32_e32 v11, v4
	v_mov_b32_e32 v12, v4
	v_mov_b32_e32 v13, v4
	v_mov_b32_e32 v14, v4
	v_mov_b32_e32 v15, v4
	v_mov_b32_e32 v16, v4
	v_mov_b32_e32 v17, v4
	v_mov_b32_e32 v18, v4
	v_mov_b32_e32 v19, v4
	v_mov_b32_e32 v20, v4
	v_mov_b32_e32 v21, v4
	v_mov_b32_e32 v22, v4
	v_mov_b32_e32 v23, v4
	v_mov_b32_e32 v24, v4
	v_mov_b32_e32 v25, v4
	v_mov_b32_e32 v26, v4
	v_mov_b32_e32 v27, v4
	v_mov_b32_e32 v28, v4
	v_mov_b32_e32 v29, v4
	v_mov_b32_e32 v30, v4
	v_mov_b32_e32 v31, v4
	v_mov_b32_e32 v32, v4
	v_mov_b32_e32 v33, v4
	v_mov_b32_e32 v34, v4
	v_mov_b32_e32 v35, v4
; DI void phase_scan(KArgs args, LAS unsigned char* L, const Ctx& c) {
;     ...
;         SCAN_DMA(); SCAN_DMA(); SCAN_DMA(); SCAN_DMA(); SCAN_DMA();
;         asm volatile("s_waitcnt vmcnt(48)" ::: "memory"); SCAN_LOAD(0);
;         asm volatile("s_waitcnt vmcnt(36)" ::: "memory"); SCAN_LOAD(1);
;         for (int step = 0; step < nch; step += 2) {
;             SCAN_STEP(0, step);     asm volatile("s_waitcnt vmcnt(24)" ::: "memory"); SCAN_LOAD(0); SCAN_DMA();
;             SCAN_STEP(1, step + 1); asm volatile("s_waitcnt vmcnt(24)" ::: "memory"); SCAN_LOAD(1); SCAN_DMA();
.LBB0_649:
	s_add_i32 s14, s10, -6
	s_add_i32 s13, s10, -1
	s_lshr_b32 s6, s14, 6
	s_cmp_lt_u32 s14, 64
	s_cselect_b64 vcc, -1, 0
	s_cmp_eq_u32 s6, 1
	s_cselect_b64 s[4:5], -1, 0
	s_cmp_eq_u32 s6, 2
	s_cselect_b64 s[6:7], -1, 0
	v_cndmask_b32_e64 v172, v170, v169, s[6:7]
	v_cndmask_b32_e64 v172, v172, v168, s[4:5]
	v_cndmask_b32_e32 v172, v172, v1, vcc
	s_waitcnt lgkmcnt(0)
	v_lshlrev_b32_e32 v174, 16, v96
	v_readlane_b32 s4, v172, s14
	v_and_b32_e32 v175, 0xffff0000, v96
	v_lshlrev_b32_e32 v96, 16, v97
	v_and_b32_e32 v97, 0xffff0000, v97
	v_cvt_pk_bf16_f32 v133, v6, v7
	v_pk_fma_f32 v[6:7], v[6:7], s[4:5], v[96:97] op_sel_hi:[1,0,1]
	v_lshlrev_b32_e32 v96, 16, v98
	v_and_b32_e32 v97, 0xffff0000, v98
	v_cvt_pk_bf16_f32 v134, v8, v9
	v_pk_fma_f32 v[8:9], v[8:9], s[4:5], v[96:97] op_sel_hi:[1,0,1]
	v_lshlrev_b32_e32 v96, 16, v99
	v_and_b32_e32 v97, 0xffff0000, v99
	v_cvt_pk_bf16_f32 v135, v10, v11
	v_pk_fma_f32 v[10:11], v[10:11], s[4:5], v[96:97] op_sel_hi:[1,0,1]
	v_lshlrev_b32_e32 v96, 16, v92
	v_and_b32_e32 v97, 0xffff0000, v92
	v_lshlrev_b32_e32 v92, 16, v93
	v_and_b32_e32 v93, 0xffff0000, v93
	v_cvt_pk_bf16_f32 v137, v14, v15
	v_pk_fma_f32 v[14:15], v[14:15], s[4:5], v[92:93] op_sel_hi:[1,0,1]
	v_lshlrev_b32_e32 v92, 16, v94
	v_and_b32_e32 v93, 0xffff0000, v94
	v_cvt_pk_bf16_f32 v138, v16, v17
	v_pk_fma_f32 v[16:17], v[16:17], s[4:5], v[92:93] op_sel_hi:[1,0,1]
	v_lshlrev_b32_e32 v92, 16, v95
	v_and_b32_e32 v93, 0xffff0000, v95
	v_cvt_pk_bf16_f32 v132, v4, v5
	v_cvt_pk_bf16_f32 v136, v12, v13
	v_cvt_pk_bf16_f32 v139, v18, v19
	v_pk_fma_f32 v[4:5], v[4:5], s[4:5], v[174:175] op_sel_hi:[1,0,1]
	v_pk_fma_f32 v[12:13], v[12:13], s[4:5], v[96:97] op_sel_hi:[1,0,1]
	v_pk_fma_f32 v[18:19], v[18:19], s[4:5], v[92:93] op_sel_hi:[1,0,1]
	v_cvt_pk_bf16_f32 v141, v22, v23
	v_cvt_pk_bf16_f32 v142, v24, v25
	v_mfma_f32_32x32x16_bf16 v[4:19], v[76:79], v[132:135], v[4:19]
	v_lshlrev_b32_e32 v76, 16, v72
	v_and_b32_e32 v77, 0xffff0000, v72
	v_lshlrev_b32_e32 v72, 16, v73
	v_and_b32_e32 v73, 0xffff0000, v73
	v_fma_f32 v22, v22, s4, v72
	v_fma_f32 v23, v23, s4, v73
	v_lshlrev_b32_e32 v72, 16, v74
	v_and_b32_e32 v73, 0xffff0000, v74
	v_pk_fma_f32 v[24:25], v[24:25], s[4:5], v[72:73] op_sel_hi:[1,0,1]
	v_lshlrev_b32_e32 v72, 16, v75
	v_and_b32_e32 v73, 0xffff0000, v75
	v_cvt_pk_bf16_f32 v143, v26, v27
	v_pk_fma_f32 v[26:27], v[26:27], s[4:5], v[72:73] op_sel_hi:[1,0,1]
	v_lshlrev_b32_e32 v72, 16, v52
	v_and_b32_e32 v73, 0xffff0000, v52
	v_lshlrev_b32_e32 v52, 16, v53
	v_and_b32_e32 v53, 0xffff0000, v53
	v_cvt_pk_bf16_f32 v145, v30, v31
	v_pk_fma_f32 v[30:31], v[30:31], s[4:5], v[52:53] op_sel_hi:[1,0,1]
	v_lshlrev_b32_e32 v52, 16, v54
	v_and_b32_e32 v53, 0xffff0000, v54
	v_cvt_pk_bf16_f32 v146, v32, v33
	v_pk_fma_f32 v[32:33], v[32:33], s[4:5], v[52:53] op_sel_hi:[1,0,1]
	v_lshlrev_b32_e32 v52, 16, v55
	v_and_b32_e32 v53, 0xffff0000, v55
	v_cvt_pk_bf16_f32 v140, v20, v21
	v_cvt_pk_bf16_f32 v144, v28, v29
	v_cvt_pk_bf16_f32 v147, v34, v35
	v_pk_fma_f32 v[20:21], v[20:21], s[4:5], v[76:77] op_sel_hi:[1,0,1]
	v_pk_fma_f32 v[28:29], v[28:29], s[4:5], v[72:73] op_sel_hi:[1,0,1]
	v_pk_fma_f32 v[34:35], v[34:35], s[4:5], v[52:53] op_sel_hi:[1,0,1]
	v_mfma_f32_32x32x16_bf16 v[4:19], v[80:83], v[136:139], v[4:19]
	s_mul_i32 s4, s12, 0x3000
	v_add_u32_e32 v52, s4, v171
	s_min_i32 s4, s13, s31
	s_ashr_i32 s5, s4, 31
	s_mul_i32 s5, s0, s5
	s_mul_hi_u32 s7, s0, s4
	s_add_i32 s5, s7, s5
	v_mfma_f32_32x32x16_bf16 v[20:35], v[36:39], v[132:135], v[20:35]
	s_mul_i32 s7, s1, s4
	s_add_i32 s6, s12, 1
	s_add_i32 s5, s5, s7
	s_mul_i32 s4, s0, s4
	s_add_u32 s4, s2, s4
	s_mul_i32 s7, s11, 0x3000
	global_store_dwordx4 v[166:167], v[132:135], off offset:-2048
	global_store_dwordx4 v[166:167], v[136:139], off offset:-1024
	global_store_dwordx4 v[166:167], v[140:143], off
	global_store_dwordx4 v[166:167], v[144:147], off offset:1024
	v_mfma_f32_32x32x16_bf16 v[20:35], v[40:43], v[136:139], v[20:35]
	s_addc_u32 s5, s3, s5
	s_add_i32 s7, s22, s7
	s_waitcnt vmcnt(36)
	v_lshl_add_u64 v[132:133], s[4:5], 0, v[2:3]
	s_mov_b32 m0, s7
	v_and_b32_e32 v173, 0xffff0000, v128
	v_lshl_add_u64 v[174:175], v[166:167], 0, s[0:1]
	v_mfma_f32_32x32x16_bf16 v[4:19], v[84:87], v[140:143], v[4:19]
	v_lshl_add_u64 v[166:167], v[166:167], 0, s[8:9]
	v_mfma_f32_32x32x16_bf16 v[20:35], v[44:47], v[140:143], v[20:35]
	v_mfma_f32_32x32x16_bf16 v[4:19], v[88:91], v[144:147], v[4:19]
	v_mfma_f32_32x32x16_bf16 v[20:35], v[48:51], v[144:147], v[20:35]
	ds_read_b128 v[76:79], v52
	ds_read_b128 v[80:83], v52 offset:1024
	ds_read_b128 v[84:87], v52 offset:2048
	ds_read_b128 v[88:91], v52 offset:3072
	ds_read_b128 v[96:99], v52 offset:8192
	ds_read_b128 v[92:95], v52 offset:9216
	ds_read_b128 v[36:39], v52 offset:4096
	ds_read_b128 v[40:43], v52 offset:5120
	ds_read_b128 v[44:47], v52 offset:6144
	ds_read_b128 v[48:51], v52 offset:7168
	ds_read_b128 v[72:75], v52 offset:10240
	ds_read_b128 v[52:55], v52 offset:11264
	global_load_lds_dwordx4 v[132:133], off
	v_lshl_add_u64 v[132:133], s[4:5], 0, v[148:149]
	s_add_i32 m0, s7, 0x400
	v_cvt_pk_bf16_f32 v134, v8, v9
	global_load_lds_dwordx4 v[132:133], off
	v_lshl_add_u64 v[132:133], s[4:5], 0, v[150:151]
	s_add_i32 m0, s7, 0x800
	v_cvt_pk_bf16_f32 v135, v10, v11
	global_load_lds_dwordx4 v[132:133], off
	v_lshl_add_u64 v[132:133], s[4:5], 0, v[152:153]
	s_add_i32 m0, s7, 0xc00
	v_cvt_pk_bf16_f32 v137, v14, v15
	global_load_lds_dwordx4 v[132:133], off
	v_lshl_add_u64 v[132:133], s[4:5], 0, v[154:155]
	s_add_i32 m0, s7, 0x1000
	v_cvt_pk_bf16_f32 v138, v16, v17
	global_load_lds_dwordx4 v[132:133], off
	v_lshl_add_u64 v[132:133], s[4:5], 0, v[156:157]
	s_add_i32 m0, s7, 0x1400
; DI void phase_scan(KArgs args, LAS unsigned char* L, const Ctx& c) {
;     ...
;         SCAN_DMA(); SCAN_DMA(); SCAN_DMA(); SCAN_DMA(); SCAN_DMA();
;         asm volatile("s_waitcnt vmcnt(48)" ::: "memory"); SCAN_LOAD(0);
;         asm volatile("s_waitcnt vmcnt(36)" ::: "memory"); SCAN_LOAD(1);
;         for (int step = 0; step < nch; step += 2) {
;             SCAN_STEP(0, step);     asm volatile("s_waitcnt vmcnt(24)" ::: "memory"); SCAN_LOAD(0); SCAN_DMA();
;             SCAN_STEP(1, step + 1); asm volatile("s_waitcnt vmcnt(24)" ::: "memory"); SCAN_LOAD(1); SCAN_DMA();
;         }
;         asm volatile("s_waitcnt vmcnt(0)" ::: "memory");
	v_cvt_pk_bf16_f32 v136, v12, v13
	global_load_lds_dwordx4 v[132:133], off
	v_lshl_add_u64 v[132:133], s[4:5], 0, v[158:159]
	s_add_i32 m0, s7, 0x1800
	v_cvt_pk_bf16_f32 v139, v18, v19
	global_load_lds_dwordx4 v[132:133], off
	s_add_i32 m0, s7, 0x1c00
	v_lshl_add_u64 v[132:133], s[4:5], 0, v[160:161]
	s_add_u32 s4, s4, 0x2000
	s_addc_u32 s5, s5, 0
	global_load_lds_dwordx4 v[132:133], off
	s_add_i32 m0, s7, 0x2000
	v_lshl_add_u64 v[132:133], s[4:5], 0, v[162:163]
	global_load_lds_dwordx4 v[132:133], off
	v_lshl_add_u64 v[132:133], v[132:133], 0, 16
	s_add_i32 m0, s7, 0x2400
	v_cvt_pk_bf16_f32 v140, v20, v21
	global_load_lds_dwordx4 v[132:133], off
	v_lshl_add_u64 v[132:133], s[4:5], 0, v[164:165]
	s_add_i32 m0, s7, 0x2800
	v_cvt_pk_bf16_f32 v141, v22, v23
	global_load_lds_dwordx4 v[132:133], off
	s_add_i32 m0, s7, 0x2c00
	s_cmp_lg_u32 s12, 4
	s_cselect_b32 s6, s6, 0
	s_add_i32 s4, s11, 1
	s_cmp_lg_u32 s11, 4
	s_cselect_b32 s7, s4, 0
	s_add_i32 s4, s10, -5
	v_lshl_add_u64 v[132:133], v[132:133], 0, 16
	v_readlane_b32 s4, v172, s4
	v_lshlrev_b32_e32 v172, 16, v128
	v_lshlrev_b32_e32 v128, 16, v129
	v_and_b32_e32 v129, 0xffff0000, v129
	global_load_lds_dwordx4 v[132:133], off
	v_cvt_pk_bf16_f32 v133, v6, v7
	v_pk_fma_f32 v[6:7], v[6:7], s[4:5], v[128:129] op_sel_hi:[1,0,1]
	v_lshlrev_b32_e32 v128, 16, v130
	v_and_b32_e32 v129, 0xffff0000, v130
	v_pk_fma_f32 v[8:9], v[8:9], s[4:5], v[128:129] op_sel_hi:[1,0,1]
	v_lshlrev_b32_e32 v128, 16, v131
	v_and_b32_e32 v129, 0xffff0000, v131
	v_pk_fma_f32 v[10:11], v[10:11], s[4:5], v[128:129] op_sel_hi:[1,0,1]
	v_lshlrev_b32_e32 v128, 16, v124
	v_and_b32_e32 v129, 0xffff0000, v124
	v_lshlrev_b32_e32 v124, 16, v125
	v_and_b32_e32 v125, 0xffff0000, v125
	v_pk_fma_f32 v[14:15], v[14:15], s[4:5], v[124:125] op_sel_hi:[1,0,1]
	v_lshlrev_b32_e32 v124, 16, v126
	v_and_b32_e32 v125, 0xffff0000, v126
	v_pk_fma_f32 v[16:17], v[16:17], s[4:5], v[124:125] op_sel_hi:[1,0,1]
	v_lshlrev_b32_e32 v124, 16, v127
	v_and_b32_e32 v125, 0xffff0000, v127
	v_cvt_pk_bf16_f32 v132, v4, v5
	v_pk_fma_f32 v[4:5], v[4:5], s[4:5], v[172:173] op_sel_hi:[1,0,1]
	v_pk_fma_f32 v[12:13], v[12:13], s[4:5], v[128:129] op_sel_hi:[1,0,1]
	v_pk_fma_f32 v[18:19], v[18:19], s[4:5], v[124:125] op_sel_hi:[1,0,1]
	v_cvt_pk_bf16_f32 v142, v24, v25
	v_cvt_pk_bf16_f32 v143, v26, v27
	v_mfma_f32_32x32x16_bf16 v[4:19], v[120:123], v[132:135], v[4:19]
	v_cvt_pk_bf16_f32 v144, v28, v29
	v_cvt_pk_bf16_f32 v145, v30, v31
	v_cvt_pk_bf16_f32 v146, v32, v33
	v_cvt_pk_bf16_f32 v147, v34, v35
	s_add_i32 s11, s6, 1
	global_store_dwordx4 v[174:175], v[132:135], off offset:-2048
	global_store_dwordx4 v[174:175], v[136:139], off offset:-1024
	global_store_dwordx4 v[174:175], v[140:143], off
	global_store_dwordx4 v[174:175], v[144:147], off offset:1024
	s_waitcnt vmcnt(36)
	v_mfma_f32_32x32x16_bf16 v[4:19], v[116:119], v[136:139], v[4:19]
	v_mfma_f32_32x32x16_bf16 v[4:19], v[112:115], v[140:143], v[4:19]
	v_mfma_f32_32x32x16_bf16 v[4:19], v[108:111], v[144:147], v[4:19]
	v_lshlrev_b32_e32 v108, 16, v104
	v_and_b32_e32 v109, 0xffff0000, v104
	v_lshlrev_b32_e32 v104, 16, v105
	v_and_b32_e32 v105, 0xffff0000, v105
	v_fma_f32 v22, v22, s4, v104
	v_fma_f32 v23, v23, s4, v105
	v_lshlrev_b32_e32 v104, 16, v106
	v_and_b32_e32 v105, 0xffff0000, v106
	v_pk_fma_f32 v[24:25], v[24:25], s[4:5], v[104:105] op_sel_hi:[1,0,1]
	v_lshlrev_b32_e32 v104, 16, v107
	v_and_b32_e32 v105, 0xffff0000, v107
	v_pk_fma_f32 v[26:27], v[26:27], s[4:5], v[104:105] op_sel_hi:[1,0,1]
	v_lshlrev_b32_e32 v104, 16, v100
	v_and_b32_e32 v105, 0xffff0000, v100
	v_lshlrev_b32_e32 v100, 16, v101
	v_and_b32_e32 v101, 0xffff0000, v101
	v_pk_fma_f32 v[30:31], v[30:31], s[4:5], v[100:101] op_sel_hi:[1,0,1]
	v_lshlrev_b32_e32 v100, 16, v102
	v_and_b32_e32 v101, 0xffff0000, v102
	v_pk_fma_f32 v[32:33], v[32:33], s[4:5], v[100:101] op_sel_hi:[1,0,1]
	v_lshlrev_b32_e32 v100, 16, v103
	v_and_b32_e32 v101, 0xffff0000, v103
	v_pk_fma_f32 v[20:21], v[20:21], s[4:5], v[108:109] op_sel_hi:[1,0,1]
	v_pk_fma_f32 v[28:29], v[28:29], s[4:5], v[104:105] op_sel_hi:[1,0,1]
	v_pk_fma_f32 v[34:35], v[34:35], s[4:5], v[100:101] op_sel_hi:[1,0,1]
	s_mul_i32 s4, s6, 0x3000
	v_add_u32_e32 v100, s4, v171
	v_mfma_f32_32x32x16_bf16 v[20:35], v[68:71], v[132:135], v[20:35]
	s_min_i32 s4, s10, s31
	s_ashr_i32 s5, s4, 31
	s_mul_i32 s5, s0, s5
	s_mul_hi_u32 s12, s0, s4
	s_add_i32 s5, s12, s5
	s_mul_i32 s12, s1, s4
	s_add_i32 s5, s5, s12
	v_mfma_f32_32x32x16_bf16 v[20:35], v[64:67], v[136:139], v[20:35]
	s_mul_i32 s4, s0, s4
	s_add_u32 s4, s2, s4
	s_mul_i32 s12, s7, 0x3000
	s_addc_u32 s5, s3, s5
	s_add_i32 s12, s22, s12
	v_lshl_add_u64 v[132:133], s[4:5], 0, v[2:3]
	s_mov_b32 m0, s12
	v_mfma_f32_32x32x16_bf16 v[20:35], v[60:63], v[140:143], v[20:35]
	v_mfma_f32_32x32x16_bf16 v[20:35], v[56:59], v[144:147], v[20:35]
	ds_read_b128 v[120:123], v100
	ds_read_b128 v[116:119], v100 offset:1024
	ds_read_b128 v[112:115], v100 offset:2048
	ds_read_b128 v[108:111], v100 offset:3072
	ds_read_b128 v[128:131], v100 offset:8192
	ds_read_b128 v[124:127], v100 offset:9216
	ds_read_b128 v[68:71], v100 offset:4096
	ds_read_b128 v[64:67], v100 offset:5120
	ds_read_b128 v[60:63], v100 offset:6144
	ds_read_b128 v[56:59], v100 offset:7168
	ds_read_b128 v[104:107], v100 offset:10240
	ds_read_b128 v[100:103], v100 offset:11264
	global_load_lds_dwordx4 v[132:133], off
	v_lshl_add_u64 v[132:133], s[4:5], 0, v[148:149]
	s_add_i32 m0, s12, 0x400
	s_nop 0
	global_load_lds_dwordx4 v[132:133], off
	v_lshl_add_u64 v[132:133], s[4:5], 0, v[150:151]
	s_add_i32 m0, s12, 0x800
	s_nop 0
	global_load_lds_dwordx4 v[132:133], off
	v_lshl_add_u64 v[132:133], s[4:5], 0, v[152:153]
	s_add_i32 m0, s12, 0xc00
	s_nop 0
	global_load_lds_dwordx4 v[132:133], off
	v_lshl_add_u64 v[132:133], s[4:5], 0, v[154:155]
	s_add_i32 m0, s12, 0x1000
	s_nop 0
	global_load_lds_dwordx4 v[132:133], off
	v_lshl_add_u64 v[132:133], s[4:5], 0, v[156:157]
	s_add_i32 m0, s12, 0x1400
	s_nop 0
	global_load_lds_dwordx4 v[132:133], off
	v_lshl_add_u64 v[132:133], s[4:5], 0, v[158:159]
	s_add_i32 m0, s12, 0x1800
	s_nop 0
	global_load_lds_dwordx4 v[132:133], off
	s_add_i32 m0, s12, 0x1c00
	v_lshl_add_u64 v[132:133], s[4:5], 0, v[160:161]
	s_add_u32 s4, s4, 0x2000
	s_addc_u32 s5, s5, 0
	global_load_lds_dwordx4 v[132:133], off
	s_add_i32 m0, s12, 0x2000
	v_lshl_add_u64 v[132:133], s[4:5], 0, v[162:163]
	global_load_lds_dwordx4 v[132:133], off
	v_lshl_add_u64 v[132:133], v[132:133], 0, 16
	s_add_i32 m0, s12, 0x2400
	s_nop 0
	global_load_lds_dwordx4 v[132:133], off
	v_lshl_add_u64 v[132:133], s[4:5], 0, v[164:165]
	s_add_i32 m0, s12, 0x2800
	s_nop 0
	global_load_lds_dwordx4 v[132:133], off
	v_lshl_add_u64 v[132:133], v[132:133], 0, 16
	s_add_i32 m0, s12, 0x2c00
	s_cmp_lg_u32 s6, 4
	global_load_lds_dwordx4 v[132:133], off
	s_cselect_b32 s12, s11, 0
	s_add_i32 s4, s7, 1
	s_cmp_lg_u32 s7, 4
	s_cselect_b32 s11, s4, 0
	s_add_i32 s4, s10, 2
	s_add_i32 s5, s10, -4
	s_cmp_ge_u32 s5, s30
	s_mov_b32 s10, s4
	s_cbranch_scc0 .LBB0_649
	s_waitcnt vmcnt(0)
	s_setprio 0
